# accumulator zeroing at unit start done with 64 v_mov_b64 instead of 128 v_mov_b32 (7 GEMM instances); on top of R6
# baseline (speedup 1.0000x reference)
.LBB0_903:
	s_ashr_i32 s45, s44, 31
	s_lshl_b64 s[48:49], s[44:45], 20
	s_add_u32 s0, s10, s48
	s_addc_u32 s1, s11, s49
	s_ashr_i32 s41, s40, 31
	s_lshl_b64 s[50:51], s[40:41], 1
	s_add_u32 s48, s0, s50
	s_addc_u32 s49, s1, s51
	s_and_b64 s[58:59], s[46:47], exec
	s_cselect_b32 s41, s49, s9
	s_cselect_b32 s45, s48, s8
	s_ashr_i32 s43, s42, 31
	s_lshl_b64 s[58:59], s[42:43], 20
	s_add_u32 s0, s2, s58
	s_addc_u32 s1, s3, s59
	s_add_u32 s50, s0, s50
	s_addc_u32 s51, s1, s51
	s_and_b64 s[58:59], s[46:47], exec
	s_cselect_b32 s43, s51, s53
	s_cselect_b32 s65, s50, s52
	s_add_i32 s66, s62, -2
	s_add_u32 s67, s52, 0x100
	s_addc_u32 s68, s53, 0
	s_add_u32 s52, s8, 0x80080
	v_mov_b64_e32 v[2:3], 0
	s_addc_u32 s53, s9, 0
	s_mov_b32 s8, 0
	v_mov_b64_e32 v[4:5], 0
	v_mov_b64_e32 v[6:7], 0
	v_mov_b64_e32 v[8:9], 0
	v_mov_b64_e32 v[10:11], 0
	v_mov_b64_e32 v[12:13], 0
	v_mov_b64_e32 v[14:15], 0
	v_mov_b64_e32 v[16:17], 0
	v_mov_b64_e32 v[18:19], 0
	v_mov_b64_e32 v[20:21], 0
	v_mov_b64_e32 v[22:23], 0
	v_mov_b64_e32 v[24:25], 0
	v_mov_b64_e32 v[26:27], 0
	v_mov_b64_e32 v[28:29], 0
	v_mov_b64_e32 v[30:31], 0
	v_mov_b64_e32 v[32:33], 0
	v_mov_b64_e32 v[34:35], 0
	v_mov_b64_e32 v[36:37], 0
	v_mov_b64_e32 v[38:39], 0
	v_mov_b64_e32 v[40:41], 0
	v_mov_b64_e32 v[42:43], 0
	v_mov_b64_e32 v[44:45], 0
	v_mov_b64_e32 v[46:47], 0
	v_mov_b64_e32 v[48:49], 0
	v_mov_b64_e32 v[50:51], 0
	v_mov_b64_e32 v[52:53], 0
	v_mov_b64_e32 v[54:55], 0
	v_mov_b64_e32 v[56:57], 0
	v_mov_b64_e32 v[58:59], 0
	v_mov_b64_e32 v[60:61], 0
	v_mov_b64_e32 v[62:63], 0
	v_mov_b64_e32 v[64:65], 0
	v_mov_b64_e32 v[66:67], 0
	v_mov_b64_e32 v[68:69], 0
	v_mov_b64_e32 v[70:71], 0
	v_mov_b64_e32 v[72:73], 0
	v_mov_b64_e32 v[74:75], 0
	v_mov_b64_e32 v[76:77], 0
	v_mov_b64_e32 v[78:79], 0
	v_mov_b64_e32 v[80:81], 0
	v_mov_b64_e32 v[82:83], 0
	v_mov_b64_e32 v[84:85], 0
	v_mov_b64_e32 v[86:87], 0
	v_mov_b64_e32 v[88:89], 0
	v_mov_b64_e32 v[90:91], 0
	v_mov_b64_e32 v[92:93], 0
	v_mov_b64_e32 v[94:95], 0
	v_mov_b64_e32 v[96:97], 0
	v_mov_b64_e32 v[98:99], 0
	v_mov_b64_e32 v[100:101], 0
	v_mov_b64_e32 v[102:103], 0
	v_mov_b64_e32 v[104:105], 0
	s_nop 0
	v_mov_b64_e32 v[106:107], 0
	v_mov_b64_e32 v[108:109], 0
	v_mov_b64_e32 v[110:111], 0
	v_mov_b64_e32 v[112:113], 0
	v_mov_b64_e32 v[114:115], 0
	v_mov_b64_e32 v[116:117], 0
	v_mov_b64_e32 v[118:119], 0
	v_mov_b64_e32 v[120:121], 0
	v_mov_b64_e32 v[122:123], 0
	v_mov_b64_e32 v[124:125], 0
	v_mov_b64_e32 v[126:127], 0
	v_mov_b64_e32 v[128:129], 0
	s_cmp_eq_u32 s100, 1
	s_cbranch_scc0 .Ldefbar_skip_0
	s_mov_b32 s100, 0
	s_barrier

.LBB0_986:
	s_add_i32 s41, s69, -2
	s_add_u32 s70, s8, 0x100
	v_mov_b64_e32 v[2:3], 0
	s_addc_u32 s71, s9, 0
	s_mov_b32 s50, 0
	v_mov_b64_e32 v[4:5], 0
	v_mov_b64_e32 v[6:7], 0
	v_mov_b64_e32 v[8:9], 0
	v_mov_b64_e32 v[10:11], 0
	v_mov_b64_e32 v[12:13], 0
	v_mov_b64_e32 v[14:15], 0
	v_mov_b64_e32 v[16:17], 0
	v_mov_b64_e32 v[18:19], 0
	v_mov_b64_e32 v[20:21], 0
	v_mov_b64_e32 v[22:23], 0
	v_mov_b64_e32 v[24:25], 0
	v_mov_b64_e32 v[26:27], 0
	v_mov_b64_e32 v[28:29], 0
	v_mov_b64_e32 v[30:31], 0
	v_mov_b64_e32 v[32:33], 0
	v_mov_b64_e32 v[34:35], 0
	v_mov_b64_e32 v[36:37], 0
	v_mov_b64_e32 v[38:39], 0
	v_mov_b64_e32 v[40:41], 0
	v_mov_b64_e32 v[42:43], 0
	v_mov_b64_e32 v[44:45], 0
	v_mov_b64_e32 v[46:47], 0
	v_mov_b64_e32 v[48:49], 0
	s_nop 0
	v_mov_b64_e32 v[50:51], 0
	v_mov_b64_e32 v[52:53], 0
	v_mov_b64_e32 v[54:55], 0
	v_mov_b64_e32 v[56:57], 0
	v_mov_b64_e32 v[58:59], 0
	v_mov_b64_e32 v[60:61], 0
	v_mov_b64_e32 v[62:63], 0
	v_mov_b64_e32 v[64:65], 0
	v_mov_b64_e32 v[66:67], 0
	v_mov_b64_e32 v[68:69], 0
	v_mov_b64_e32 v[70:71], 0
	v_mov_b64_e32 v[72:73], 0
	v_mov_b64_e32 v[74:75], 0
	v_mov_b64_e32 v[76:77], 0
	v_mov_b64_e32 v[78:79], 0
	v_mov_b64_e32 v[80:81], 0
	v_mov_b64_e32 v[82:83], 0
	v_mov_b64_e32 v[84:85], 0
	v_mov_b64_e32 v[86:87], 0
	v_mov_b64_e32 v[88:89], 0
	v_mov_b64_e32 v[90:91], 0
	v_mov_b64_e32 v[92:93], 0
	v_mov_b64_e32 v[94:95], 0
	v_mov_b64_e32 v[96:97], 0
	v_mov_b64_e32 v[98:99], 0
	v_mov_b64_e32 v[100:101], 0
	v_mov_b64_e32 v[102:103], 0
	v_mov_b64_e32 v[104:105], 0
	v_mov_b64_e32 v[106:107], 0
	v_mov_b64_e32 v[108:109], 0
	v_mov_b64_e32 v[110:111], 0
	v_mov_b64_e32 v[112:113], 0
	v_mov_b64_e32 v[114:115], 0
	v_mov_b64_e32 v[116:117], 0
	v_mov_b64_e32 v[118:119], 0
	v_mov_b64_e32 v[120:121], 0
	v_mov_b64_e32 v[122:123], 0
	v_mov_b64_e32 v[124:125], 0
	v_mov_b64_e32 v[126:127], 0
	v_mov_b64_e32 v[128:129], 0
	s_cmp_eq_u32 s100, 1
	s_cbranch_scc0 .Ldefbar_skip_1
	s_mov_b32 s100, 0
	s_barrier

.LBB0_1134:
	s_ashr_i32 s47, s46, 31
	s_lshl_b64 s[50:51], s[46:47], 20
	s_add_u32 s0, s2, s50
	s_addc_u32 s1, s3, s51
	s_ashr_i32 s43, s42, 31
	s_lshl_b64 s[52:53], s[42:43], 1
	s_add_u32 s50, s0, s52
	s_addc_u32 s51, s1, s53
	s_and_b64 s[62:63], s[48:49], exec
	s_cselect_b32 s43, s51, s9
	s_cselect_b32 s47, s50, s8
	s_ashr_i32 s45, s44, 31
	s_lshl_b64 s[62:63], s[44:45], 20
	s_add_u32 s0, s10, s62
	s_addc_u32 s1, s11, s63
	s_add_u32 s52, s0, s52
	s_addc_u32 s53, s1, s53
	s_and_b64 s[62:63], s[48:49], exec
	s_cselect_b32 s45, s53, s59
	s_cselect_b32 s67, s52, s58
	s_add_i32 s68, s64, -2
	s_add_u32 s69, s58, 0x100
	s_addc_u32 s70, s59, 0
	s_add_u32 s58, s8, 0x80080
	v_mov_b64_e32 v[2:3], 0
	s_addc_u32 s59, s9, 0
	s_mov_b32 s8, 0
	v_mov_b64_e32 v[4:5], 0
	v_mov_b64_e32 v[6:7], 0
	v_mov_b64_e32 v[8:9], 0
	v_mov_b64_e32 v[10:11], 0
	v_mov_b64_e32 v[12:13], 0
	v_mov_b64_e32 v[14:15], 0
	v_mov_b64_e32 v[16:17], 0
	v_mov_b64_e32 v[18:19], 0
	v_mov_b64_e32 v[20:21], 0
	v_mov_b64_e32 v[22:23], 0
	v_mov_b64_e32 v[24:25], 0
	v_mov_b64_e32 v[26:27], 0
	v_mov_b64_e32 v[28:29], 0
	v_mov_b64_e32 v[30:31], 0
	v_mov_b64_e32 v[32:33], 0
	v_mov_b64_e32 v[34:35], 0
	v_mov_b64_e32 v[36:37], 0
	v_mov_b64_e32 v[38:39], 0
	v_mov_b64_e32 v[40:41], 0
	v_mov_b64_e32 v[42:43], 0
	v_mov_b64_e32 v[44:45], 0
	v_mov_b64_e32 v[46:47], 0
	v_mov_b64_e32 v[48:49], 0
	v_mov_b64_e32 v[50:51], 0
	v_mov_b64_e32 v[52:53], 0
	v_mov_b64_e32 v[54:55], 0
	v_mov_b64_e32 v[56:57], 0
	v_mov_b64_e32 v[58:59], 0
	v_mov_b64_e32 v[60:61], 0
	v_mov_b64_e32 v[62:63], 0
	v_mov_b64_e32 v[64:65], 0
	v_mov_b64_e32 v[66:67], 0
	v_mov_b64_e32 v[68:69], 0
	v_mov_b64_e32 v[70:71], 0
	v_mov_b64_e32 v[72:73], 0
	v_mov_b64_e32 v[74:75], 0
	v_mov_b64_e32 v[76:77], 0
	v_mov_b64_e32 v[78:79], 0
	v_mov_b64_e32 v[80:81], 0
	v_mov_b64_e32 v[82:83], 0
	v_mov_b64_e32 v[84:85], 0
	v_mov_b64_e32 v[86:87], 0
	v_mov_b64_e32 v[88:89], 0
	v_mov_b64_e32 v[90:91], 0
	v_mov_b64_e32 v[92:93], 0
	v_mov_b64_e32 v[94:95], 0
	v_mov_b64_e32 v[96:97], 0
	s_nop 0
	v_mov_b64_e32 v[98:99], 0
	v_mov_b64_e32 v[100:101], 0
	v_mov_b64_e32 v[102:103], 0
	v_mov_b64_e32 v[104:105], 0
	v_mov_b64_e32 v[106:107], 0
	v_mov_b64_e32 v[108:109], 0
	v_mov_b64_e32 v[110:111], 0
	v_mov_b64_e32 v[112:113], 0
	v_mov_b64_e32 v[114:115], 0
	v_mov_b64_e32 v[116:117], 0
	v_mov_b64_e32 v[118:119], 0
	v_mov_b64_e32 v[120:121], 0
	v_mov_b64_e32 v[122:123], 0
	v_mov_b64_e32 v[124:125], 0
	v_mov_b64_e32 v[126:127], 0
	v_mov_b64_e32 v[128:129], 0
	s_cmp_eq_u32 s100, 1
	s_cbranch_scc0 .Ldefbar_skip_2
	s_mov_b32 s100, 0
	s_barrier

.LBB0_2238:
	s_ashr_i32 s53, s52, 31
	s_lshl_b64 s[0:1], s[52:53], 21
	s_add_u32 s49, s38, s0
	s_addc_u32 s53, s39, s1
	s_ashr_i32 s51, s50, 31
	s_lshl_b64 s[0:1], s[50:51], 1
	s_add_u32 s62, s49, s0
	s_addc_u32 s63, s53, s1
	s_and_b64 s[64:65], s[58:59], exec
	s_cselect_b32 s51, s63, s9
	s_cselect_b32 s53, s62, s8
	s_ashr_i32 s49, s48, 31
	s_lshl_b64 s[64:65], s[48:49], 21
	s_add_u32 s49, s40, s64
	s_addc_u32 s65, s41, s65
	s_add_u32 s64, s49, s0
	s_addc_u32 s65, s65, s1
	s_and_b64 s[0:1], s[58:59], exec
	s_cselect_b32 s49, s65, s45
	s_cselect_b32 s69, s64, s44
	s_add_i32 s70, s35, -2
	s_add_u32 s71, s44, 0x100
	s_addc_u32 s72, s45, 0
	s_add_u32 s44, s8, 0x100080
	v_mov_b64_e32 v[2:3], 0
	s_addc_u32 s45, s9, 0
	s_mov_b32 s8, 0
	v_mov_b64_e32 v[4:5], 0
	v_mov_b64_e32 v[6:7], 0
	v_mov_b64_e32 v[8:9], 0
	v_mov_b64_e32 v[10:11], 0
	v_mov_b64_e32 v[12:13], 0
	v_mov_b64_e32 v[14:15], 0
	v_mov_b64_e32 v[16:17], 0
	v_mov_b64_e32 v[18:19], 0
	v_mov_b64_e32 v[20:21], 0
	v_mov_b64_e32 v[22:23], 0
	v_mov_b64_e32 v[24:25], 0
	v_mov_b64_e32 v[26:27], 0
	v_mov_b64_e32 v[28:29], 0
	v_mov_b64_e32 v[30:31], 0
	v_mov_b64_e32 v[32:33], 0
	v_mov_b64_e32 v[34:35], 0
	v_mov_b64_e32 v[36:37], 0
	v_mov_b64_e32 v[38:39], 0
	v_mov_b64_e32 v[40:41], 0
	v_mov_b64_e32 v[42:43], 0
	v_mov_b64_e32 v[44:45], 0
	v_mov_b64_e32 v[46:47], 0
	v_mov_b64_e32 v[48:49], 0
	v_mov_b64_e32 v[50:51], 0
	v_mov_b64_e32 v[52:53], 0
	v_mov_b64_e32 v[54:55], 0
	v_mov_b64_e32 v[56:57], 0
	v_mov_b64_e32 v[58:59], 0
	v_mov_b64_e32 v[60:61], 0
	v_mov_b64_e32 v[62:63], 0
	v_mov_b64_e32 v[64:65], 0
	v_mov_b64_e32 v[66:67], 0
	v_mov_b64_e32 v[68:69], 0
	v_mov_b64_e32 v[70:71], 0
	v_mov_b64_e32 v[72:73], 0
	v_mov_b64_e32 v[74:75], 0
	v_mov_b64_e32 v[76:77], 0
	v_mov_b64_e32 v[78:79], 0
	v_mov_b64_e32 v[80:81], 0
	v_mov_b64_e32 v[82:83], 0
	v_mov_b64_e32 v[84:85], 0
	v_mov_b64_e32 v[86:87], 0
	v_mov_b64_e32 v[88:89], 0
	v_mov_b64_e32 v[90:91], 0
	v_mov_b64_e32 v[92:93], 0
	v_mov_b64_e32 v[94:95], 0
	v_mov_b64_e32 v[96:97], 0
	v_mov_b64_e32 v[98:99], 0
	v_mov_b64_e32 v[100:101], 0
	v_mov_b64_e32 v[102:103], 0
	v_mov_b64_e32 v[104:105], 0
	s_nop 0
	v_mov_b64_e32 v[106:107], 0
	v_mov_b64_e32 v[108:109], 0
	v_mov_b64_e32 v[110:111], 0
	v_mov_b64_e32 v[112:113], 0
	v_mov_b64_e32 v[114:115], 0
	v_mov_b64_e32 v[116:117], 0
	v_mov_b64_e32 v[118:119], 0
	v_mov_b64_e32 v[120:121], 0
	v_mov_b64_e32 v[122:123], 0
	v_mov_b64_e32 v[124:125], 0
	v_mov_b64_e32 v[126:127], 0
	v_mov_b64_e32 v[128:129], 0
	s_cmp_eq_u32 s100, 1
	s_cbranch_scc0 .Ldefbar_skip_3
	s_mov_b32 s100, 0
	s_barrier

.LBB0_2356:
	s_ashr_i32 s45, s44, 31
	s_lshl_b64 s[0:1], s[44:45], 20
	s_add_u32 s43, s2, s0
	s_addc_u32 s45, s3, s1
	s_ashr_i32 s41, s40, 31
	s_lshl_b64 s[0:1], s[40:41], 1
	s_add_u32 s48, s43, s0
	s_addc_u32 s49, s45, s1
	s_and_b64 s[50:51], s[46:47], exec
	s_cselect_b32 s41, s49, s63
	s_cselect_b32 s45, s48, s62
	s_ashr_i32 s43, s42, 31
	s_lshl_b64 s[50:51], s[42:43], 20
	s_add_u32 s43, s10, s50
	s_addc_u32 s51, s11, s51
	s_add_u32 s50, s43, s0
	s_addc_u32 s51, s51, s1
	s_and_b64 s[0:1], s[46:47], exec
	s_cselect_b32 s43, s51, s9
	s_cselect_b32 s70, s50, s8
	s_add_i32 s71, s69, -2
	s_add_u32 s72, s8, 0x100
	s_addc_u32 s73, s9, 0
	s_add_u32 s62, s62, 0x80080
	v_mov_b64_e32 v[2:3], 0
	s_addc_u32 s63, s63, 0
	s_mov_b32 s8, 0
	v_mov_b64_e32 v[4:5], 0
	v_mov_b64_e32 v[6:7], 0
	v_mov_b64_e32 v[8:9], 0
	v_mov_b64_e32 v[10:11], 0
	v_mov_b64_e32 v[12:13], 0
	v_mov_b64_e32 v[14:15], 0
	v_mov_b64_e32 v[16:17], 0
	v_mov_b64_e32 v[18:19], 0
	v_mov_b64_e32 v[20:21], 0
	v_mov_b64_e32 v[22:23], 0
	v_mov_b64_e32 v[24:25], 0
	v_mov_b64_e32 v[26:27], 0
	v_mov_b64_e32 v[28:29], 0
	v_mov_b64_e32 v[30:31], 0
	v_mov_b64_e32 v[32:33], 0
	v_mov_b64_e32 v[34:35], 0
	v_mov_b64_e32 v[36:37], 0
	v_mov_b64_e32 v[38:39], 0
	v_mov_b64_e32 v[40:41], 0
	v_mov_b64_e32 v[42:43], 0
	v_mov_b64_e32 v[44:45], 0
	v_mov_b64_e32 v[46:47], 0
	v_mov_b64_e32 v[48:49], 0
	s_nop 0
	v_mov_b64_e32 v[50:51], 0
	v_mov_b64_e32 v[52:53], 0
	v_mov_b64_e32 v[54:55], 0
	v_mov_b64_e32 v[56:57], 0
	v_mov_b64_e32 v[58:59], 0
	v_mov_b64_e32 v[60:61], 0
	v_mov_b64_e32 v[62:63], 0
	v_mov_b64_e32 v[64:65], 0
	v_mov_b64_e32 v[66:67], 0
	v_mov_b64_e32 v[68:69], 0
	v_mov_b64_e32 v[70:71], 0
	v_mov_b64_e32 v[72:73], 0
	v_mov_b64_e32 v[74:75], 0
	v_mov_b64_e32 v[76:77], 0
	v_mov_b64_e32 v[78:79], 0
	v_mov_b64_e32 v[80:81], 0
	v_mov_b64_e32 v[82:83], 0
	v_mov_b64_e32 v[84:85], 0
	v_mov_b64_e32 v[86:87], 0
	v_mov_b64_e32 v[88:89], 0
	v_mov_b64_e32 v[90:91], 0
	v_mov_b64_e32 v[92:93], 0
	v_mov_b64_e32 v[94:95], 0
	v_mov_b64_e32 v[96:97], 0
	v_mov_b64_e32 v[98:99], 0
	v_mov_b64_e32 v[100:101], 0
	v_mov_b64_e32 v[102:103], 0
	v_mov_b64_e32 v[104:105], 0
	v_mov_b64_e32 v[106:107], 0
	v_mov_b64_e32 v[108:109], 0
	v_mov_b64_e32 v[110:111], 0
	v_mov_b64_e32 v[112:113], 0
	v_mov_b64_e32 v[114:115], 0
	v_mov_b64_e32 v[116:117], 0
	v_mov_b64_e32 v[118:119], 0
	v_mov_b64_e32 v[120:121], 0
	v_mov_b64_e32 v[122:123], 0
	v_mov_b64_e32 v[124:125], 0
	v_mov_b64_e32 v[126:127], 0
	v_mov_b64_e32 v[128:129], 0
	s_cmp_eq_u32 s100, 1
	s_cbranch_scc0 .Ldefbar_skip_4
	s_mov_b32 s100, 0
	s_barrier

.LBB0_2506:
	s_ashr_i32 s45, s44, 31
	s_lshl_b64 s[0:1], s[44:45], 20
	s_add_u32 s43, s2, s0
	s_addc_u32 s45, s3, s1
	s_ashr_i32 s41, s40, 31
	s_lshl_b64 s[0:1], s[40:41], 1
	s_add_u32 s48, s43, s0
	s_addc_u32 s49, s45, s1
	s_and_b64 s[50:51], s[46:47], exec
	s_cselect_b32 s41, s49, s9
	s_cselect_b32 s45, s48, s8
	s_ashr_i32 s43, s42, 31
	s_lshl_b64 s[50:51], s[42:43], 20
	s_add_u32 s43, s10, s50
	s_addc_u32 s51, s11, s51
	s_add_u32 s50, s43, s0
	s_addc_u32 s51, s51, s1
	s_and_b64 s[0:1], s[46:47], exec
	s_cselect_b32 s43, s51, s53
	s_cselect_b32 s65, s50, s52
	s_add_i32 s66, s62, -2
	s_add_u32 s67, s52, 0x100
	s_addc_u32 s68, s53, 0
	s_add_u32 s52, s8, 0x80080
	v_mov_b64_e32 v[2:3], 0
	s_addc_u32 s53, s9, 0
	s_mov_b32 s8, 0
	v_mov_b64_e32 v[4:5], 0
	v_mov_b64_e32 v[6:7], 0
	v_mov_b64_e32 v[8:9], 0
	v_mov_b64_e32 v[10:11], 0
	v_mov_b64_e32 v[12:13], 0
	v_mov_b64_e32 v[14:15], 0
	v_mov_b64_e32 v[16:17], 0
	v_mov_b64_e32 v[18:19], 0
	v_mov_b64_e32 v[20:21], 0
	v_mov_b64_e32 v[22:23], 0
	v_mov_b64_e32 v[24:25], 0
	v_mov_b64_e32 v[26:27], 0
	v_mov_b64_e32 v[28:29], 0
	v_mov_b64_e32 v[30:31], 0
	v_mov_b64_e32 v[32:33], 0
	v_mov_b64_e32 v[34:35], 0
	v_mov_b64_e32 v[36:37], 0
	v_mov_b64_e32 v[38:39], 0
	v_mov_b64_e32 v[40:41], 0
	v_mov_b64_e32 v[42:43], 0
	v_mov_b64_e32 v[44:45], 0
	v_mov_b64_e32 v[46:47], 0
	v_mov_b64_e32 v[48:49], 0
	v_mov_b64_e32 v[50:51], 0
	v_mov_b64_e32 v[52:53], 0
	v_mov_b64_e32 v[54:55], 0
	v_mov_b64_e32 v[56:57], 0
	v_mov_b64_e32 v[58:59], 0
	v_mov_b64_e32 v[60:61], 0
	v_mov_b64_e32 v[62:63], 0
	v_mov_b64_e32 v[64:65], 0
	v_mov_b64_e32 v[66:67], 0
	v_mov_b64_e32 v[68:69], 0
	v_mov_b64_e32 v[70:71], 0
	v_mov_b64_e32 v[72:73], 0
	v_mov_b64_e32 v[74:75], 0
	v_mov_b64_e32 v[76:77], 0
	v_mov_b64_e32 v[78:79], 0
	v_mov_b64_e32 v[80:81], 0
	v_mov_b64_e32 v[82:83], 0
	v_mov_b64_e32 v[84:85], 0
	v_mov_b64_e32 v[86:87], 0
	v_mov_b64_e32 v[88:89], 0
	v_mov_b64_e32 v[90:91], 0
	v_mov_b64_e32 v[92:93], 0
	v_mov_b64_e32 v[94:95], 0
	v_mov_b64_e32 v[96:97], 0
	v_mov_b64_e32 v[98:99], 0
	v_mov_b64_e32 v[100:101], 0
	v_mov_b64_e32 v[102:103], 0
	v_mov_b64_e32 v[104:105], 0
	v_mov_b64_e32 v[106:107], 0
	v_mov_b64_e32 v[108:109], 0
	v_mov_b64_e32 v[110:111], 0
	v_mov_b64_e32 v[112:113], 0
	v_mov_b64_e32 v[114:115], 0
	v_mov_b64_e32 v[116:117], 0
	v_mov_b64_e32 v[118:119], 0
	v_mov_b64_e32 v[120:121], 0
	v_mov_b64_e32 v[122:123], 0
	v_mov_b64_e32 v[124:125], 0
	v_mov_b64_e32 v[126:127], 0
	v_mov_b64_e32 v[128:129], 0
	s_cmp_eq_u32 s100, 1
	s_cbranch_scc0 .Ldefbar_skip_5
	s_mov_b32 s100, 0
	s_barrier

.LBB0_2587:
	s_add_i32 s41, s69, -2
	s_add_u32 s70, s8, 0x100
	v_mov_b64_e32 v[2:3], 0
	s_addc_u32 s71, s9, 0
	s_mov_b32 s48, 0
	v_mov_b64_e32 v[4:5], 0
	v_mov_b64_e32 v[6:7], 0
	v_mov_b64_e32 v[8:9], 0
	v_mov_b64_e32 v[10:11], 0
	v_mov_b64_e32 v[12:13], 0
	v_mov_b64_e32 v[14:15], 0
	v_mov_b64_e32 v[16:17], 0
	v_mov_b64_e32 v[18:19], 0
	v_mov_b64_e32 v[20:21], 0
	v_mov_b64_e32 v[22:23], 0
	v_mov_b64_e32 v[24:25], 0
	v_mov_b64_e32 v[26:27], 0
	v_mov_b64_e32 v[28:29], 0
	v_mov_b64_e32 v[30:31], 0
	v_mov_b64_e32 v[32:33], 0
	v_mov_b64_e32 v[34:35], 0
	v_mov_b64_e32 v[36:37], 0
	v_mov_b64_e32 v[38:39], 0
	v_mov_b64_e32 v[40:41], 0
	v_mov_b64_e32 v[42:43], 0
	v_mov_b64_e32 v[44:45], 0
	v_mov_b64_e32 v[46:47], 0
	v_mov_b64_e32 v[48:49], 0
	s_nop 0
	v_mov_b64_e32 v[50:51], 0
	v_mov_b64_e32 v[52:53], 0
	v_mov_b64_e32 v[54:55], 0
	v_mov_b64_e32 v[56:57], 0
	v_mov_b64_e32 v[58:59], 0
	v_mov_b64_e32 v[60:61], 0
	v_mov_b64_e32 v[62:63], 0
	v_mov_b64_e32 v[64:65], 0
	v_mov_b64_e32 v[66:67], 0
	v_mov_b64_e32 v[68:69], 0
	v_mov_b64_e32 v[70:71], 0
	v_mov_b64_e32 v[72:73], 0
	v_mov_b64_e32 v[74:75], 0
	v_mov_b64_e32 v[76:77], 0
	v_mov_b64_e32 v[78:79], 0
	v_mov_b64_e32 v[80:81], 0
	v_mov_b64_e32 v[82:83], 0
	v_mov_b64_e32 v[84:85], 0
	v_mov_b64_e32 v[86:87], 0
	v_mov_b64_e32 v[88:89], 0
	v_mov_b64_e32 v[90:91], 0
	v_mov_b64_e32 v[92:93], 0
	v_mov_b64_e32 v[94:95], 0
	v_mov_b64_e32 v[96:97], 0
	v_mov_b64_e32 v[98:99], 0
	v_mov_b64_e32 v[100:101], 0
	v_mov_b64_e32 v[102:103], 0
	v_mov_b64_e32 v[104:105], 0
	v_mov_b64_e32 v[106:107], 0
	v_mov_b64_e32 v[108:109], 0
	v_mov_b64_e32 v[110:111], 0
	v_mov_b64_e32 v[112:113], 0
	v_mov_b64_e32 v[114:115], 0
	v_mov_b64_e32 v[116:117], 0
	v_mov_b64_e32 v[118:119], 0
	v_mov_b64_e32 v[120:121], 0
	v_mov_b64_e32 v[122:123], 0
	v_mov_b64_e32 v[124:125], 0
	v_mov_b64_e32 v[126:127], 0
	v_mov_b64_e32 v[128:129], 0
	s_cmp_eq_u32 s100, 1
	s_cbranch_scc0 .Ldefbar_skip_6
	s_mov_b32 s100, 0
	s_barrier
